# unrolled K-loops plus one-period (s_sleep 53) phase-start offset for blocks with blockIdx bit 8 at the four GEMM phase starts
# baseline (speedup 1.0000x reference)
; __global__ void __launch_bounds__(NTHREADS, 2) mega_kernel(Params p) {
;     ...
;         for (int rep = 0; rep < REP_GEMM; ++rep) {
;             EpiIn epi;
;             epi.P = (bf16_t*)(p.ws + OFF_P); epi.VTA = (bf16_t*)(p.ws + OFF_VTA); epi.VTC = (bf16_t*)(p.ws + OFF_VTC);
;             epi.FT = (bf16_t*)(p.ws + OFF_FT); epi.G = (float*)(p.ws + OFF_G);
;             const int nbx = (int)(gridDim.x >> 3), xg = bid & 7, jb = bid >> 3;
;             constexpr int TOT = (NTOK / 256) * 23, PERX = TOT / 8;
;             const int nround = PERX / nbx, nrem = PERX - nround * nbx;
;             auto tile_of = [&](int idx, int& tm, int& tn) {
;                 const int g = xg * PERX + idx, rg = g / 184; int r = g - rg * 184;
;                 if (r < 128) { tm = rg * 8 + ((r & 63) >> 3); tn = (r >> 6) * 8 + (r & 7); }
;                 else { r -= 128; tm = rg * 8 + r / 7; tn = 16 + r % 7; }
;             };
;             const bf16_t* Wl = WinT + (size_t)l * NPAD * 1024;
;             bool pref = false;
;             for (int rd = 0; rd < nround; ++rd) {
;                 int mt, nt, mt2 = 0, nt2 = 0;
;                 tile_of(rd * nbx + jb, mt, nt);
;                 const bool have2 = (rd + 1 < nround);
;                 if (have2) tile_of((rd + 1) * nbx + jb, mt2, nt2);
;                 if (nt >= 14 && nt < 22) gemm_tile_ring<8, false>(HM, 1024, Wl, 1024, 1024, mt * 256, nt * 128, lds, epi, pref, have2, mt2 * 256, nt2 * 128);
;                 else gemm_tile_ring<8, true>(HM, 1024, Wl, 1024, 1024, mt * 256, nt * 128, lds, epi, pref, have2, mt2 * 256, nt2 * 128);
.LBB0_250:
	s_or_b64 exec, exec, s[0:1]
	s_mul_i32 s18, s52, 0x2e0000
	v_readlane_b32 s4, v248, 47
	s_lshl_b64 s[0:1], s[18:19], 1
	v_readlane_b32 s8, v248, 51
	v_readlane_b32 s9, v248, 52
	s_add_u32 s2, s8, s0
	s_addc_u32 s3, s9, s1
	v_readlane_b32 s0, v250, 48
	v_readlane_b32 s1, v250, 49
	s_andn2_b64 vcc, exec, s[0:1]
	s_mul_hi_u32 s34, s52, 0x5c0000
	s_mul_i32 s35, s52, 0x5c0000
	s_waitcnt lgkmcnt(0)
	s_barrier
	s_cselect_b32 s99, 1, 0
	v_readlane_b32 s98, v248, 0
	s_nop 3
	s_bitcmp1_b32 s98, 8
	s_cbranch_scc0 .Lphstag_skip_B
	s_sleep 53
.Lphstag_skip_B:
	s_cmp_lg_u32 s99, 0
	v_readlane_b32 s5, v248, 48
	v_readlane_b32 s6, v248, 49
	v_readlane_b32 s7, v248, 50
	v_readlane_b32 s10, v248, 53
	v_readlane_b32 s11, v248, 54
	s_cbranch_vccnz .LBB0_858
	v_readlane_b32 s0, v251, 18
	s_add_u32 s12, s0, s35
	v_readlane_b32 s0, v251, 19
	s_addc_u32 s13, s0, s34
	s_mov_b32 s36, 0
	s_mov_b64 s[0:1], 0
	s_branch .LBB0_254

; __global__ void __launch_bounds__(NTHREADS, 2) mega_kernel(Params p) {
;     ...
;         const int Mrows = last ? NLAT : NTOK;
;         {
;             EpiRes epi; epi.srcLat = srcLat; epi.srcCtx = srcCtx; epi.dstLat = p.out; epi.dstCtx = ctxres;
;             epi.mod = modall + (size_t)l * 17 * 6144; epi.gidx = 2;
;             int it = 0, mt, nt; bool have = next_tile(it, NLAT / 256, 8, mt, nt), pref = false;
;             while (have) {
;                 int it2 = it + 1, mt2 = 0, nt2 = 0; const bool have2 = next_tile(it2, NLAT / 256, 8, mt2, nt2);
;                 gemm_tile_ring<8, true>(HM, 1024, WoutT + (size_t)l * 1024 * 1024, 1024, 1024, mt * 256, nt * 128, lds, epi, pref, have2, mt2 * 256, nt2 * 128);
.LBB0_1927:
	s_or_b64 exec, exec, s[0:1]
	v_readlane_b32 s0, v250, 55
	v_readlane_b32 s1, v250, 56
	s_andn2_b64 vcc, exec, s[0:1]
	s_waitcnt lgkmcnt(0)
	v_cndmask_b32_e64 v0, 0, 1, s[0:1]
	v_readlane_b32 s0, v250, 59
	v_cmp_ne_u32_e64 s[2:3], 1, v0
	v_readlane_b32 s1, v250, 60
	s_barrier
	s_cselect_b32 s99, 1, 0
	v_readlane_b32 s98, v248, 0
	s_nop 3
	s_bitcmp1_b32 s98, 8
	s_cbranch_scc0 .Lphstag_skip_G
	s_sleep 53
.Lphstag_skip_G:
	s_cmp_lg_u32 s99, 0
	v_writelane_b32 v252, s2, 34
	v_cndmask_b32_e64 v0, 0, 1, s[0:1]
	v_cmp_ne_u32_e64 s[76:77], 1, v0
	v_writelane_b32 v252, s3, 35
	s_cbranch_vccnz .LBB0_1933
	s_and_b64 vcc, exec, s[76:77]
	s_cbranch_vccnz .LBB0_1934
	v_readlane_b32 s0, v250, 61
	s_mov_b32 s18, 8
	v_readlane_b32 s1, v250, 62
	v_readlane_b32 s2, v250, 63
	v_readlane_b32 s3, v251, 0
	v_readlane_b32 s4, v251, 1
	v_readlane_b32 s5, v251, 2
	v_readlane_b32 s6, v251, 3
	v_readlane_b32 s7, v251, 4
	v_readlane_b32 s33, v251, 54
	v_readlane_b32 s36, v251, 7
	v_readlane_b32 s37, v251, 43
	v_readlane_b32 s38, v251, 44
	v_readlane_b32 s39, v251, 45
	v_readlane_b32 s41, v251, 46
	v_readlane_b32 s44, v251, 47
	v_readlane_b32 s45, v251, 48
	v_readlane_b32 s46, v251, 49
	v_readlane_b32 s47, v251, 50
	v_readlane_b32 s48, v251, 51
	v_readlane_b32 s49, v251, 52
	v_readlane_b32 s50, v251, 53
	v_readlane_b32 s51, v251, 55

; __device__ __forceinline__ bool tile_map(int it, int MT, int NT, int& mt, int& nt) {
;     const int xcd = blockIdx.x & 7, j = blockIdx.x >> 3, SR = (int)(gridDim.x >> 6);
;     const int ncg = (NT + 7) >> 3, nrg = (MT + SR - 1) / SR;
;     const int s = xcd + 8 * it;
;     if (s >= nrg * ncg) return false;
;     const int rg = s / ncg, cgi = s - rg * ncg;
;     mt = rg * SR + (j >> 3); nt = cgi * 8 + (j & 7);
;     return true;
; }
; __device__ __forceinline__ bool next_tile(int& it, int MT, int NT, int& mt, int& nt) {
;     while (tile_map(it, MT, NT, mt, nt)) { if (mt < MT && nt < NT) return true; ++it; }
;     return false;
; __global__ void __launch_bounds__(NTHREADS, 2) mega_kernel(Params p) {
;     ...
;         for (int rep = 0; rep < REP_GEMM; ++rep) {
;             EpiFF1 epi; epi.HID = (bf16_t*)(p.ws + OFF_HID);
;             int it = 0, mt, nt; bool have = next_tile(it, Mrows / 256, 32, mt, nt), pref = false;
;             while (have) {
;                 int it2 = it + 1, mt2 = 0, nt2 = 0; const bool have2 = next_tile(it2, Mrows / 256, 32, mt2, nt2);
;                 gemm_tile_ring<8, true>(HM, 1024, W1T + (size_t)l * 4096 * 1024, 1024, 1024, mt * 256, nt * 128, lds, epi, pref, have2, mt2 * 256, nt2 * 128);
.LBB0_2143:
	v_writelane_b32 v253, s25, 46
	s_or_b64 exec, exec, s[0:1]
	s_lshr_b32 s18, s16, 8
	v_readlane_b32 s0, v250, 47
	s_add_i32 s0, s0, s18
	v_readlane_b32 s1, v251, 8
	s_mul_hi_u32 s1, s0, s1
	s_mul_i32 s2, s1, s56
	s_sub_i32 s0, s0, s2
	s_add_i32 s2, s1, 1
	s_sub_i32 s3, s0, s56
	s_cmp_ge_u32 s0, s56
	s_cselect_b32 s1, s2, s1
	s_cselect_b32 s0, s3, s0
	s_add_i32 s2, s1, 1
	s_cmp_ge_u32 s0, s56
	s_cselect_b32 s0, s2, s1
	s_lshl_b32 s33, s0, 2
	v_readlane_b32 s0, v250, 61
	v_writelane_b32 v252, s73, 36
	s_cmp_ge_u32 s0, s33
	v_writelane_b32 v252, s74, 39
	s_waitcnt lgkmcnt(0)
	s_barrier
	s_cselect_b32 s99, 1, 0
	v_readlane_b32 s98, v248, 0
	s_nop 3
	s_bitcmp1_b32 s98, 8
	s_cbranch_scc0 .Lphstag_skip_I
	s_sleep 53
.Lphstag_skip_I:
	s_cmp_lg_u32 s99, 0
	v_readlane_b32 s1, v250, 62
	v_readlane_b32 s2, v250, 63
	v_readlane_b32 s3, v251, 0
	v_readlane_b32 s4, v251, 1
	v_readlane_b32 s5, v251, 2
	v_readlane_b32 s6, v251, 3
	v_readlane_b32 s7, v251, 4
	s_cbranch_scc1 .LBB0_2149
	v_readlane_b32 s0, v250, 57
	s_add_i32 s0, s33, s0
	s_cmpk_lt_u32 s0, 0xb8
	s_cbranch_scc1 .LBB0_2150
	s_lshr_b32 s0, s0, 3
	v_writelane_b32 v252, s76, 40
	s_add_i32 s44, s0, 1
	v_readlane_b32 s0, v250, 61
	v_writelane_b32 v252, s77, 41
	s_and_b32 s28, s44, 0x3ffffff8
	s_mov_b32 s48, s18
	s_mov_b32 s49, s18
	s_mov_b32 s50, s18
	s_mov_b32 s51, s18
	s_mov_b32 s52, s18
	s_mov_b32 s53, s18
	s_mov_b32 s54, s18
	s_mov_b32 s29, 8
	v_readlane_b32 s1, v250, 62
	v_readlane_b32 s2, v250, 63
	v_readlane_b32 s3, v251, 0
	v_readlane_b32 s4, v251, 1
	v_readlane_b32 s5, v251, 2
	v_readlane_b32 s6, v251, 3
	v_readlane_b32 s7, v251, 4
	s_mov_b32 s95, s56
	v_readlane_b32 s36, v251, 54
	v_readlane_b32 s37, v251, 60
	v_readlane_b32 s38, v251, 43
	v_readlane_b32 s39, v251, 44
	v_readlane_b32 s40, v251, 45
	v_readlane_b32 s41, v251, 46
	v_readlane_b32 s46, v251, 47
	v_readlane_b32 s47, v251, 48
	v_readlane_b32 s96, v251, 49
	v_readlane_b32 s97, v251, 50
	v_readlane_b32 s78, v251, 51
	v_readlane_b32 s80, v251, 52
	v_readlane_b32 s82, v251, 53
	v_readlane_b32 s84, v251, 55
	v_readlane_b32 s86, v251, 56
	v_readlane_b32 s79, v251, 57
	v_readlane_b32 s88, v251, 58
	v_readlane_b32 s89, v251, 59
	v_readlane_b32 s90, v251, 61

; __global__ void __launch_bounds__(NTHREADS, 2) mega_kernel(Params p) {
;     ...
;         {
;             EpiRes epi; epi.srcLat = p.out; epi.srcCtx = ctxres; epi.dstLat = p.out; epi.dstCtx = ctxres;
;             epi.mod = modall + (size_t)l * 17 * 6144; epi.gidx = 5;
;             int it = 0, mt, nt; bool have = next_tile(it, NLAT / 256, 8, mt, nt), pref = false;
;             while (have) {
;                 int it2 = it + 1, mt2 = 0, nt2 = 0; const bool have2 = next_tile(it2, NLAT / 256, 8, mt2, nt2);
;                 gemm_tile_ring<8, true>((const bf16_t*)(p.ws + OFF_HID), 4096, W2T + (size_t)l * 1024 * 4096, 4096, 4096, mt * 256, nt * 128, lds, epi, pref, have2, mt2 * 256, nt2 * 128);
.LBB0_2260:
	s_or_b64 exec, exec, s[0:1]
	v_readlane_b32 s0, v252, 34
	v_readlane_b32 s1, v252, 35
	s_and_b64 vcc, exec, s[0:1]
	s_waitcnt lgkmcnt(0)
	s_barrier
	s_cselect_b32 s99, 1, 0
	v_readlane_b32 s98, v248, 0
	s_nop 3
	s_bitcmp1_b32 s98, 8
	s_cbranch_scc0 .Lphstag_skip_J
	s_sleep 53
.Lphstag_skip_J:
	s_cmp_lg_u32 s99, 0
	s_cbranch_vccnz .LBB0_2266
	s_and_b64 vcc, exec, s[76:77]
	s_cbranch_vccnz .LBB0_2267
	v_readlane_b32 s0, v250, 61
	s_mov_b32 s18, 8
	v_readlane_b32 s1, v250, 62
	v_readlane_b32 s2, v250, 63
	v_readlane_b32 s3, v251, 0
	v_readlane_b32 s4, v251, 1
	v_readlane_b32 s5, v251, 2
	v_readlane_b32 s6, v251, 3
	v_readlane_b32 s7, v251, 4
	v_readlane_b32 s33, v251, 54
	v_readlane_b32 s39, v251, 7
	v_readlane_b32 s44, v251, 43
	v_readlane_b32 s45, v251, 44
	v_readlane_b32 s40, v251, 45
	v_readlane_b32 s41, v251, 46
	v_readlane_b32 s46, v251, 47
	v_readlane_b32 s47, v251, 48
	v_readlane_b32 s48, v251, 49
	v_readlane_b32 s49, v251, 50
	v_readlane_b32 s50, v251, 51
	v_readlane_b32 s51, v251, 52
	v_readlane_b32 s12, v251, 53
	v_readlane_b32 s13, v251, 55
